# m20 plus threshold test on per-lane maxima (cross-half exchange only on the rescale path)
# baseline (speedup 1.0000x reference)
; #define LAS __attribute__((address_space(3)))
; __device__ __forceinline__ float swap_max(float m) { auto rr = __builtin_amdgcn_permlane32_swap(__float_as_uint(m), __float_as_uint(m), false, false); return fmaxf(__uint_as_float(rr[0]), __uint_as_float(rr[1])); }
; #define MLA_PACK(P, b) (u32x4){cvt_pk_bf16(P[b], P[b + 1]), cvt_pk_bf16(P[b + 2], P[b + 3]), cvt_pk_bf16(P[b + 4], P[b + 5]), cvt_pk_bf16(P[b + 6], P[b + 7])}
; __device__ __forceinline__ float max2_(float a, float b) { return __builtin_amdgcn_fmed3f(a, b, INFINITY); }
; __device__ __forceinline__ void softmax_blk(f32x16& p0, f32x16& p1, f32x16& o0, f32x16& o1, float& mhat, float& lrun, u32x4 (&pf)[4], bool first) {
;     float r0 = max2_(p0[0], p0[1]), r1 = max2_(p1[0], p1[1]);
; #pragma unroll
;     for (int e = 2; e < 16; ++e) { r0 = max2_(r0, p0[e]); r1 = max2_(r1, p1[e]); }
;     const float rm = swap_max(max2_(r0, r1));
;     if (first || __any(rm - mhat > THR)) {
;         const float mn = first ? rm : fmaxf(rm, mhat); const float f = first ? 0.f : __builtin_amdgcn_exp2f(mhat - mn); mhat = mn; lrun *= f;
; #pragma unroll
;         for (int e = 0; e < 16; ++e) { o0[e] *= f; o1[e] *= f; }
;     }
;     float s0 = 0.f, s1 = 0.f;
; #pragma unroll
;     for (int e = 0; e < 16; ++e) { p0[e] = __builtin_amdgcn_exp2f(p0[e] - mhat); p1[e] = __builtin_amdgcn_exp2f(p1[e] - mhat); s0 += p0[e]; s1 += p1[e]; }
;     lrun += s0 + s1;
;     pf[0] = MLA_PACK(p0, 0); pf[1] = MLA_PACK(p0, 8); pf[2] = MLA_PACK(p1, 0); pf[3] = MLA_PACK(p1, 8);
; }
; __device__ __forceinline__ void attn_unit(const bf16_t* Qh, const bf16_t* Kh, const bf16_t* Vh, bf16_t* Oh  , int S, int qb, LAS unsigned char* lds, int tid) {
;     ...
;             for (int s = 0; s < 6; ++s) {
;                 const bf16x8 a0 = *(const LAS bf16x8*)(lds + cur + kfo + s * 32), a1 = *(const LAS bf16x8*)(lds + cur + kfo + 32 * KPITCH + s * 32);
;                 const bf16x8 q = *(const LAS bf16x8*)(ql + s * 1024);
;                 p0 = __builtin_amdgcn_mfma_f32_32x32x16_bf16(a0, q, p0, 0, 0, 0); p1 = __builtin_amdgcn_mfma_f32_32x32x16_bf16(a1, q, p1, 0, 0, 0);
;             }
;             softmax_blk(p0, p1, oa0, oa1, ma, la, pf, t == 0);
.Lmla_nok1p:
	s_add_u32 s26, s26, 0x3000
	s_addc_u32 s27, s27, 0
	s_waitcnt lgkmcnt(3)
	v_mfma_f32_32x32x16_bf16 v[64:79], v[176:179], v[186:189], v[64:79]
	v_mfma_f32_32x32x16_bf16 v[80:95], v[180:183], v[186:189], v[80:95]
	ds_read_b128 v[176:179], v155 offset:96
	ds_read_b128 v[180:183], v155 offset:6752
	ds_read_b128 v[186:189], v135 offset:46080
	s_waitcnt lgkmcnt(3)
	v_mfma_f32_32x32x16_bf16 v[64:79], v[128:131], v[162:165], v[64:79]
	v_mfma_f32_32x32x16_bf16 v[80:95], v[142:145], v[162:165], v[80:95]
	ds_read_b128 v[128:131], v155 offset:128
	ds_read_b128 v[142:145], v155 offset:6784
	ds_read_b128 v[162:165], v135 offset:47104
	s_waitcnt lgkmcnt(3)
	v_mfma_f32_32x32x16_bf16 v[64:79], v[176:179], v[186:189], v[64:79]
	v_mfma_f32_32x32x16_bf16 v[80:95], v[180:183], v[186:189], v[80:95]
	ds_read_b128 v[176:179], v155 offset:160
	ds_read_b128 v[180:183], v155 offset:6816
	ds_read_b128 v[186:189], v135 offset:48128
	s_waitcnt lgkmcnt(3)
	v_mfma_f32_32x32x16_bf16 v[64:79], v[128:131], v[162:165], v[64:79]
	v_mfma_f32_32x32x16_bf16 v[80:95], v[142:145], v[162:165], v[80:95]
	ds_read_b128 v[128:131], v155
	ds_read_b128 v[142:145], v155 offset:6656
	ds_read_b128 v[162:165], v135 offset:49152
	s_waitcnt lgkmcnt(3)
	v_mfma_f32_32x32x16_bf16 v[64:79], v[176:179], v[186:189], v[64:79]
	v_mfma_f32_32x32x16_bf16 v[80:95], v[180:183], v[186:189], v[80:95]
	ds_read_b128 v[176:179], v155 offset:32
	ds_read_b128 v[180:183], v155 offset:6688
	ds_read_b128 v[186:189], v135 offset:50176
	s_waitcnt lgkmcnt(3)
	v_mfma_f32_32x32x16_bf16 v[96:111], v[128:131], v[162:165], 0
	v_mfma_f32_32x32x16_bf16 v[112:127], v[142:145], v[162:165], 0
	ds_read_b128 v[128:131], v155 offset:64
	ds_read_b128 v[142:145], v155 offset:6720
	ds_read_b128 v[162:165], v135 offset:51200
	s_nop 5
	v_max3_f32 v248, v64, v65, v66
	v_max3_f32 v249, v80, v81, v82
	v_max3_f32 v248, v248, v67, v68
	v_max3_f32 v249, v249, v83, v84
	v_max3_f32 v248, v248, v69, v70
	v_max3_f32 v249, v249, v85, v86
	v_max3_f32 v248, v248, v71, v72
	v_max3_f32 v249, v249, v87, v88
	v_max3_f32 v248, v248, v73, v74
	v_max3_f32 v249, v249, v89, v90
	v_max3_f32 v248, v248, v75, v76
	v_max3_f32 v249, v249, v91, v92
	v_max3_f32 v248, v248, v77, v78
	v_max3_f32 v249, v249, v93, v94
	v_max3_f32 v248, v248, v79, v95
	v_max_f32_e32 v248, v248, v249
	v_mov_b32_e32 v251, v248
	s_nop 1
	v_permlane32_swap_b32_e32 v248, v251
	v_max_f32_e32 v167, v248, v251
	v_sub_f32_e32 v64, v64, v167
	v_sub_f32_e32 v65, v65, v167
	v_sub_f32_e32 v66, v66, v167
	v_sub_f32_e32 v67, v67, v167
	v_sub_f32_e32 v68, v68, v167
	v_sub_f32_e32 v69, v69, v167
	v_sub_f32_e32 v70, v70, v167
	v_sub_f32_e32 v71, v71, v167
	v_sub_f32_e32 v72, v72, v167
	v_sub_f32_e32 v73, v73, v167
	v_sub_f32_e32 v74, v74, v167
	v_sub_f32_e32 v75, v75, v167
	v_sub_f32_e32 v76, v76, v167
	s_waitcnt lgkmcnt(3)
	v_mfma_f32_32x32x16_bf16 v[96:111], v[176:179], v[186:189], v[96:111]
	v_mfma_f32_32x32x16_bf16 v[112:127], v[180:183], v[186:189], v[112:127]
	ds_read_b128 v[176:179], v155 offset:96
	ds_read_b128 v[180:183], v155 offset:6752
	ds_read_b128 v[186:189], v135 offset:52224
	v_sub_f32_e32 v77, v77, v167
	v_sub_f32_e32 v78, v78, v167
	v_sub_f32_e32 v79, v79, v167
	v_sub_f32_e32 v80, v80, v167
	v_sub_f32_e32 v81, v81, v167
	v_sub_f32_e32 v82, v82, v167
	v_sub_f32_e32 v83, v83, v167
	v_sub_f32_e32 v84, v84, v167
	v_sub_f32_e32 v85, v85, v167
	v_sub_f32_e32 v86, v86, v167
	v_sub_f32_e32 v87, v87, v167
	v_sub_f32_e32 v88, v88, v167
	v_sub_f32_e32 v89, v89, v167
	v_sub_f32_e32 v90, v90, v167
	v_sub_f32_e32 v91, v91, v167
	v_sub_f32_e32 v92, v92, v167
	v_sub_f32_e32 v93, v93, v167
	v_sub_f32_e32 v94, v94, v167
	v_sub_f32_e32 v95, v95, v167
	v_sub_f32_e32 v232, 0, v167
	v_sub_f32_e32 v233, 0, v167
	v_sub_f32_e32 v234, 0, v167
	v_sub_f32_e32 v235, 0, v167
	v_sub_f32_e32 v236, 0, v167
	v_sub_f32_e32 v237, 0, v167
	v_sub_f32_e32 v238, 0, v167
	v_sub_f32_e32 v239, 0, v167
	v_sub_f32_e32 v240, 0, v167
	v_sub_f32_e32 v241, 0, v167
	v_sub_f32_e32 v242, 0, v167
	v_sub_f32_e32 v243, 0, v167
	v_sub_f32_e32 v244, 0, v167
	v_sub_f32_e32 v245, 0, v167
	s_waitcnt lgkmcnt(3)
	v_mfma_f32_32x32x16_bf16 v[96:111], v[128:131], v[162:165], v[96:111]
	v_mfma_f32_32x32x16_bf16 v[112:127], v[142:145], v[162:165], v[112:127]
	ds_read_b128 v[128:131], v155 offset:128
	ds_read_b128 v[142:145], v155 offset:6784
	ds_read_b128 v[162:165], v135 offset:53248
	v_sub_f32_e32 v246, 0, v167
	v_sub_f32_e32 v247, 0, v167
	v_max3_f32 v248, v64, v65, v66
	v_max3_f32 v249, v80, v81, v82
	v_max3_f32 v248, v248, v67, v68
	v_max3_f32 v249, v249, v83, v84
	v_max3_f32 v248, v248, v69, v70
	v_max3_f32 v249, v249, v85, v86
	v_max3_f32 v248, v248, v71, v72
	v_max3_f32 v249, v249, v87, v88
	v_max3_f32 v248, v248, v73, v74
	v_max3_f32 v249, v249, v89, v90
	v_max3_f32 v248, v248, v75, v76
	v_max3_f32 v249, v249, v91, v92
	v_max3_f32 v248, v248, v77, v78
	v_max3_f32 v249, v249, v93, v94
	v_max3_f32 v248, v248, v79, v95
	v_max_f32_e32 v248, v248, v249
	v_cmp_lt_f32_e32 vcc, s72, v248
	s_cbranch_vccnz .Lmla_rescAp
; __device__ __forceinline__ void softmax_blk(f32x16& p0, f32x16& p1, f32x16& o0, f32x16& o1, float& mhat, float& lrun, u32x4 (&pf)[4], bool first) {
;     float r0 = max2_(p0[0], p0[1]), r1 = max2_(p1[0], p1[1]);
; #pragma unroll
;     for (int e = 2; e < 16; ++e) { r0 = max2_(r0, p0[e]); r1 = max2_(r1, p1[e]); }
;     const float rm = swap_max(max2_(r0, r1));
;     if (first || __any(rm - mhat > THR)) {
;         const float mn = first ? rm : fmaxf(rm, mhat); const float f = first ? 0.f : __builtin_amdgcn_exp2f(mhat - mn); mhat = mn; lrun *= f;
; #pragma unroll
;         for (int e = 0; e < 16; ++e) { o0[e] *= f; o1[e] *= f; }
;     }
;     float s0 = 0.f, s1 = 0.f;
; #pragma unroll
;     for (int e = 0; e < 16; ++e) { p0[e] = __builtin_amdgcn_exp2f(p0[e] - mhat); p1[e] = __builtin_amdgcn_exp2f(p1[e] - mhat); s0 += p0[e]; s1 += p1[e]; }
;     lrun += s0 + s1;
;     pf[0] = MLA_PACK(p0, 0); pf[1] = MLA_PACK(p0, 8); pf[2] = MLA_PACK(p1, 0); pf[3] = MLA_PACK(p1, 8);
; __device__ __forceinline__ void attn_unit(const bf16_t* Qh, const bf16_t* Kh, const bf16_t* Vh, bf16_t* Oh  , int S, int qb, LAS unsigned char* lds, int tid) {
;     ...
;             f32x16 p0 = {}, p1 = {};
; #pragma unroll
;             for (int s = 0; s < 6; ++s) {
;                 const bf16x8 a0 = *(const LAS bf16x8*)(lds + cur + kfo + s * 32), a1 = *(const LAS bf16x8*)(lds + cur + kfo + 32 * KPITCH + s * 32);
;                 const bf16x8 q = *(const LAS bf16x8*)(ql + s * 1024);
;                 p0 = __builtin_amdgcn_mfma_f32_32x32x16_bf16(a0, q, p0, 0, 0, 0); p1 = __builtin_amdgcn_mfma_f32_32x32x16_bf16(a1, q, p1, 0, 0, 0);
;             }
;             softmax_blk(p0, p1, oa0, oa1, ma, la, pf, t == 0);
;             pv_blk(pf, oa0, oa1, lds + cur + vb);
;         }
;         __builtin_amdgcn_sched_barrier(0);
;         {
;             f32x16 p0 = {}, p1 = {};
; #pragma unroll
;             for (int s = 0; s < 6; ++s) {
;                 const bf16x8 a0 = *(const LAS bf16x8*)(lds + cur + kfo + s * 32), a1 = *(const LAS bf16x8*)(lds + cur + kfo + 32 * KPITCH + s * 32);
;                 const bf16x8 q = *(const LAS bf16x8*)(ql + (6 + s) * 1024);
;                 p0 = __builtin_amdgcn_mfma_f32_32x32x16_bf16(a0, q, p0, 0, 0, 0); p1 = __builtin_amdgcn_mfma_f32_32x32x16_bf16(a1, q, p1, 0, 0, 0);
;             }
;             softmax_blk(p0, p1, ob0, ob1, mb, lb, pf, t == 0);
.Lmla_rescAp_back:
	v_exp_f32_e32 v64, v64
	v_exp_f32_e32 v65, v65
	v_exp_f32_e32 v66, v66
	v_exp_f32_e32 v67, v67
	v_exp_f32_e32 v68, v68
	v_exp_f32_e32 v69, v69
	v_exp_f32_e32 v70, v70
	s_waitcnt lgkmcnt(3)
	v_mfma_f32_32x32x16_bf16 v[96:111], v[176:179], v[186:189], v[96:111]
	v_mfma_f32_32x32x16_bf16 v[112:127], v[180:183], v[186:189], v[112:127]
	ds_read_b128 v[176:179], v155 offset:160
	ds_read_b128 v[180:183], v155 offset:6816
	ds_read_b128 v[186:189], v135 offset:54272
	v_exp_f32_e32 v71, v71
	v_add_f32_e32 v166, v64, v65
	v_add_f32_e32 v140, v140, v66
	v_add_f32_e32 v166, v166, v67
	v_cvt_pk_bf16_f32 v64, v64, v65
	v_cvt_pk_bf16_f32 v65, v66, v67
	v_exp_f32_e32 v72, v72
	v_exp_f32_e32 v73, v73
	v_exp_f32_e32 v74, v74
	v_exp_f32_e32 v75, v75
	v_add_f32_e32 v140, v140, v68
	v_add_f32_e32 v166, v166, v69
	v_add_f32_e32 v140, v140, v70
	v_add_f32_e32 v166, v166, v71
	v_cvt_pk_bf16_f32 v66, v68, v69
	v_cvt_pk_bf16_f32 v67, v70, v71
	v_exp_f32_e32 v76, v76
	v_exp_f32_e32 v77, v77
	v_exp_f32_e32 v78, v78
	v_exp_f32_e32 v79, v79
	v_add_f32_e32 v140, v140, v72
	v_add_f32_e32 v166, v166, v73
	v_add_f32_e32 v140, v140, v74
	s_waitcnt lgkmcnt(3)
	v_mfma_f32_32x32x16_bf16 v[96:111], v[128:131], v[162:165], v[96:111]
	v_mfma_f32_32x32x16_bf16 v[112:127], v[142:145], v[162:165], v[112:127]
	v_add_f32_e32 v166, v166, v75
	v_cvt_pk_bf16_f32 v68, v72, v73
	v_cvt_pk_bf16_f32 v69, v74, v75
	v_exp_f32_e32 v80, v80
	v_exp_f32_e32 v81, v81
	v_exp_f32_e32 v82, v82
	v_exp_f32_e32 v83, v83
	v_add_f32_e32 v140, v140, v76
	v_add_f32_e32 v166, v166, v77
	v_add_f32_e32 v140, v140, v78
	v_add_f32_e32 v166, v166, v79
	v_cvt_pk_bf16_f32 v70, v76, v77
	v_cvt_pk_bf16_f32 v71, v78, v79
	v_exp_f32_e32 v84, v84
	v_exp_f32_e32 v85, v85
	v_exp_f32_e32 v86, v86
	v_exp_f32_e32 v87, v87
	v_add_f32_e32 v140, v140, v80
	v_add_f32_e32 v166, v166, v81
	v_add_f32_e32 v140, v140, v82
	v_add_f32_e32 v166, v166, v83
	v_cvt_pk_bf16_f32 v72, v80, v81
	v_cvt_pk_bf16_f32 v73, v82, v83
	v_exp_f32_e32 v88, v88
	s_waitcnt lgkmcnt(0)
	v_mfma_f32_32x32x16_bf16 v[96:111], v[176:179], v[186:189], v[96:111]
	v_mfma_f32_32x32x16_bf16 v[112:127], v[180:183], v[186:189], v[112:127]
	v_exp_f32_e32 v89, v89
	v_exp_f32_e32 v90, v90
	v_exp_f32_e32 v91, v91
	v_add_f32_e32 v140, v140, v84
	v_add_f32_e32 v166, v166, v85
	v_add_f32_e32 v140, v140, v86
	v_add_f32_e32 v166, v166, v87
	v_cvt_pk_bf16_f32 v74, v84, v85
	v_cvt_pk_bf16_f32 v75, v86, v87
	v_exp_f32_e32 v92, v92
	v_exp_f32_e32 v93, v93
	v_exp_f32_e32 v94, v94
	v_exp_f32_e32 v95, v95
	v_add_f32_e32 v140, v140, v88
	v_add_f32_e32 v166, v166, v89
	v_add_f32_e32 v140, v140, v90
	v_add_f32_e32 v166, v166, v91
	v_cvt_pk_bf16_f32 v76, v88, v89
	v_cvt_pk_bf16_f32 v77, v90, v91
	v_add_f32_e32 v140, v140, v92
	v_add_f32_e32 v166, v166, v93
	v_add_f32_e32 v140, v140, v94
	v_add_f32_e32 v166, v166, v95
	v_cvt_pk_bf16_f32 v78, v92, v93
	v_cvt_pk_bf16_f32 v79, v94, v95
	v_add_f32_e32 v140, v140, v166
	s_nop 7
	s_nop 3
	v_max3_f32 v248, v96, v97, v98
	v_max3_f32 v249, v112, v113, v114
	v_max3_f32 v248, v248, v99, v100
	v_max3_f32 v249, v249, v115, v116
	v_max3_f32 v248, v248, v101, v102
	v_max3_f32 v249, v249, v117, v118
	v_max3_f32 v248, v248, v103, v104
	v_max3_f32 v249, v249, v119, v120
	v_max3_f32 v248, v248, v105, v106
	v_max3_f32 v249, v249, v121, v122
	v_max3_f32 v248, v248, v107, v108
	v_max3_f32 v249, v249, v123, v124
	v_max3_f32 v248, v248, v109, v110
	v_max3_f32 v249, v249, v125, v126
	v_max3_f32 v248, v248, v111, v127
	v_max_f32_e32 v248, v248, v249
	v_mov_b32_e32 v251, v248
	s_nop 1
	v_permlane32_swap_b32_e32 v248, v251
	v_max_f32_e32 v167, v248, v251
	v_sub_f32_e32 v96, v96, v167
	v_sub_f32_e32 v97, v97, v167
	v_sub_f32_e32 v98, v98, v167
	v_sub_f32_e32 v99, v99, v167
	v_sub_f32_e32 v100, v100, v167
	v_sub_f32_e32 v101, v101, v167
	v_sub_f32_e32 v102, v102, v167
	v_sub_f32_e32 v103, v103, v167
	v_sub_f32_e32 v104, v104, v167
	v_sub_f32_e32 v105, v105, v167
	v_sub_f32_e32 v106, v106, v167
	v_sub_f32_e32 v107, v107, v167
	v_sub_f32_e32 v108, v108, v167
	v_sub_f32_e32 v109, v109, v167
	v_sub_f32_e32 v110, v110, v167
	v_sub_f32_e32 v111, v111, v167
	v_sub_f32_e32 v112, v112, v167
	v_sub_f32_e32 v113, v113, v167
	v_sub_f32_e32 v114, v114, v167
	v_sub_f32_e32 v115, v115, v167
	v_sub_f32_e32 v116, v116, v167
	v_sub_f32_e32 v117, v117, v167
	v_sub_f32_e32 v118, v118, v167
	v_sub_f32_e32 v119, v119, v167
	v_sub_f32_e32 v120, v120, v167
	v_sub_f32_e32 v121, v121, v167
	v_sub_f32_e32 v122, v122, v167
	v_sub_f32_e32 v123, v123, v167
	v_sub_f32_e32 v124, v124, v167
	v_sub_f32_e32 v125, v125, v167
	v_sub_f32_e32 v126, v126, v167
	v_sub_f32_e32 v127, v127, v167
	v_sub_f32_e32 v190, 0, v167
	v_sub_f32_e32 v191, 0, v167
	v_sub_f32_e32 v192, 0, v167
	v_sub_f32_e32 v193, 0, v167
	v_sub_f32_e32 v194, 0, v167
	v_sub_f32_e32 v195, 0, v167
	v_sub_f32_e32 v196, 0, v167
	v_sub_f32_e32 v197, 0, v167
	v_sub_f32_e32 v198, 0, v167
	v_sub_f32_e32 v199, 0, v167
	v_sub_f32_e32 v200, 0, v167
	v_sub_f32_e32 v201, 0, v167
	v_sub_f32_e32 v202, 0, v167
	v_sub_f32_e32 v203, 0, v167
	v_sub_f32_e32 v204, 0, v167
	v_sub_f32_e32 v205, 0, v167
	s_waitcnt vmcnt(0)
	ds_write_b128 v150, v[218:221] offset:21504
	ds_write_b128 v159, v[222:225]
	s_waitcnt lgkmcnt(0)
	s_barrier

; #define LAS __attribute__((address_space(3)))
; __device__ __forceinline__ float max2_(float a, float b) { return __builtin_amdgcn_fmed3f(a, b, INFINITY); }
; __device__ __forceinline__ void softmax_blk(f32x16& p0, f32x16& p1, f32x16& o0, f32x16& o1, float& mhat, float& lrun, u32x4 (&pf)[4], bool first) {
;     float r0 = max2_(p0[0], p0[1]), r1 = max2_(p1[0], p1[1]);
; #pragma unroll
;     for (int e = 2; e < 16; ++e) { r0 = max2_(r0, p0[e]); r1 = max2_(r1, p1[e]); }
;     const float rm = swap_max(max2_(r0, r1));
;     if (first || __any(rm - mhat > THR)) {
;         const float mn = first ? rm : fmaxf(rm, mhat); const float f = first ? 0.f : __builtin_amdgcn_exp2f(mhat - mn); mhat = mn; lrun *= f;
; #pragma unroll
;         for (int e = 0; e < 16; ++e) { o0[e] *= f; o1[e] *= f; }
;     }
;     float s0 = 0.f, s1 = 0.f;
; #pragma unroll
;     for (int e = 0; e < 16; ++e) { p0[e] = __builtin_amdgcn_exp2f(p0[e] - mhat); p1[e] = __builtin_amdgcn_exp2f(p1[e] - mhat); s0 += p0[e]; s1 += p1[e]; }
;     lrun += s0 + s1;
;     pf[0] = MLA_PACK(p0, 0); pf[1] = MLA_PACK(p0, 8); pf[2] = MLA_PACK(p1, 0); pf[3] = MLA_PACK(p1, 8);
; }
; __device__ __forceinline__ void pv_blk(const u32x4 (&pf)[4], f32x16& o0, f32x16& o1, LAS const unsigned char* vbase) {
; #pragma unroll
;     for (int ks = 0; ks < 4; ++ks) {
;         const bf16x8 p = __builtin_bit_cast(bf16x8, pf[ks]);
;         { const s16x4 lo = vtr(vbase + ks * 1024), hh = vtr(vbase + ks * 1024 + 512); const bf16x8 vf = {lo[0], lo[1], lo[2], lo[3], hh[0], hh[1], hh[2], hh[3]};
;           o0 = __builtin_amdgcn_mfma_f32_32x32x16_bf16(vf, p, o0, 0, 0, 0); }
;         { const s16x4 lo = vtr(vbase + 4096 + ks * 1024), hh = vtr(vbase + 4096 + ks * 1024 + 512); const bf16x8 vf = {lo[0], lo[1], lo[2], lo[3], hh[0], hh[1], hh[2], hh[3]};
;           o1 = __builtin_amdgcn_mfma_f32_32x32x16_bf16(vf, p, o1, 0, 0, 0); }
;     }
; }
; __device__ __forceinline__ void attn_unit(const bf16_t* Qh, const bf16_t* Kh, const bf16_t* Vh, bf16_t* Oh  , int S, int qb, LAS unsigned char* lds, int tid) {
;     ...
;     for (int t = 0; t < NT; ++t) {
;         const unsigned cur = (unsigned)(t & 1) * BUF, nxt = BUF - cur;
;         const int tn = t + 1 < NT ? t + 1 : t;
;         ka = GLD(u32x4, Kg + (size_t)tn * 768 + kc0); kb = GLD(u32x4, Kg + (size_t)tn * 768 + kc1); va = GLD(u32x4, Vg + (size_t)tn * 512 + tid);
.Lmla_nok1Ao:
	global_load_dwordx4 v[226:229], v146, s[100:101]
	s_add_u32 s26, s26, 0x3000
	s_addc_u32 s27, s27, 0
	s_add_u32 s100, s100, 0x2000
	s_addc_u32 s101, s101, 0
	v_max3_f32 v248, v96, v97, v98
	v_max3_f32 v249, v112, v113, v114
	v_max3_f32 v248, v248, v99, v100
	v_max3_f32 v249, v249, v115, v116
	v_max3_f32 v248, v248, v101, v102
	v_max3_f32 v249, v249, v117, v118
	v_max3_f32 v248, v248, v103, v104
	v_max3_f32 v249, v249, v119, v120
	v_max3_f32 v248, v248, v105, v106
	v_max3_f32 v249, v249, v121, v122
	v_max3_f32 v248, v248, v107, v108
	v_max3_f32 v249, v249, v123, v124
	v_max3_f32 v248, v248, v109, v110
	s_waitcnt lgkmcnt(4)
	v_mfma_f32_32x32x16_bf16 v[16:31], v[176:179], v[68:71], v[16:31]
	v_mfma_f32_32x32x16_bf16 v[0:15], v[180:183], v[68:71], v[0:15]
	ds_read_b64_tr_b16 v[176:177], v158 offset:16384
	ds_read_b64_tr_b16 v[178:179], v158 offset:16896
	ds_read_b64_tr_b16 v[180:181], v158 offset:20480
	ds_read_b64_tr_b16 v[182:183], v158 offset:20992
	v_max3_f32 v249, v249, v125, v126
	v_max3_f32 v248, v248, v111, v127
	v_max_f32_e32 v248, v248, v249
	v_cmp_lt_f32_e32 vcc, s72, v248
	s_cbranch_vccnz .Lmla_rescBo
.Lmla_rescBo_back:
	v_exp_f32_e32 v96, v96
	v_exp_f32_e32 v97, v97
	v_exp_f32_e32 v98, v98
	v_exp_f32_e32 v99, v99
	s_waitcnt lgkmcnt(4)
	v_mfma_f32_32x32x16_bf16 v[16:31], v[128:131], v[72:75], v[16:31]
	v_mfma_f32_32x32x16_bf16 v[0:15], v[142:145], v[72:75], v[0:15]
	ds_read_b128 v[128:131], v155 offset:21504
	ds_read_b128 v[142:145], v155 offset:28160
	ds_read_b128 v[162:165], v135 offset:43008
	v_exp_f32_e32 v100, v100
	v_exp_f32_e32 v101, v101
	v_exp_f32_e32 v102, v102
	v_exp_f32_e32 v103, v103
	v_add_f32_e32 v166, v96, v97
	v_add_f32_e32 v141, v141, v98
	v_add_f32_e32 v166, v166, v99
	v_cvt_pk_bf16_f32 v96, v96, v97
	v_cvt_pk_bf16_f32 v97, v98, v99
	s_waitcnt lgkmcnt(3)
	v_mfma_f32_32x32x16_bf16 v[16:31], v[176:179], v[76:79], v[16:31]
	v_mfma_f32_32x32x16_bf16 v[0:15], v[180:183], v[76:79], v[0:15]
	ds_read_b128 v[176:179], v155 offset:21536
	ds_read_b128 v[180:183], v155 offset:28192
	ds_read_b128 v[186:189], v135 offset:44032
	v_exp_f32_e32 v104, v104
	v_exp_f32_e32 v105, v105
	v_exp_f32_e32 v106, v106
	v_exp_f32_e32 v107, v107
	v_add_f32_e32 v141, v141, v100
	v_add_f32_e32 v166, v166, v101
	v_add_f32_e32 v141, v141, v102
	v_add_f32_e32 v166, v166, v103
	v_cvt_pk_bf16_f32 v98, v100, v101
	s_waitcnt lgkmcnt(3)
	v_mfma_f32_32x32x16_bf16 v[64:79], v[128:131], v[162:165], v[232:247]
	v_mfma_f32_32x32x16_bf16 v[80:95], v[142:145], v[162:165], v[232:247]
	ds_read_b128 v[128:131], v155 offset:21568
	ds_read_b128 v[142:145], v155 offset:28224
	ds_read_b128 v[162:165], v135 offset:45056
	v_cvt_pk_bf16_f32 v99, v102, v103
	v_exp_f32_e32 v108, v108
	v_exp_f32_e32 v109, v109
	v_exp_f32_e32 v110, v110
	v_exp_f32_e32 v111, v111
	v_add_f32_e32 v141, v141, v104
	v_add_f32_e32 v166, v166, v105
	v_add_f32_e32 v141, v141, v106
	v_add_f32_e32 v166, v166, v107
	s_waitcnt lgkmcnt(3)
	v_mfma_f32_32x32x16_bf16 v[64:79], v[176:179], v[186:189], v[64:79]
	v_mfma_f32_32x32x16_bf16 v[80:95], v[180:183], v[186:189], v[80:95]
	ds_read_b128 v[176:179], v155 offset:21600
	ds_read_b128 v[180:183], v155 offset:28256
	ds_read_b128 v[186:189], v135 offset:46080
	v_cvt_pk_bf16_f32 v100, v104, v105
	v_cvt_pk_bf16_f32 v101, v106, v107
	v_exp_f32_e32 v112, v112
	v_exp_f32_e32 v113, v113
	v_exp_f32_e32 v114, v114
	v_exp_f32_e32 v115, v115
	v_add_f32_e32 v141, v141, v108
	v_add_f32_e32 v166, v166, v109
	v_add_f32_e32 v141, v141, v110
	s_waitcnt lgkmcnt(3)
	v_mfma_f32_32x32x16_bf16 v[64:79], v[128:131], v[162:165], v[64:79]
	v_mfma_f32_32x32x16_bf16 v[80:95], v[142:145], v[162:165], v[80:95]
	ds_read_b128 v[128:131], v155 offset:21632
	ds_read_b128 v[142:145], v155 offset:28288
	ds_read_b128 v[162:165], v135 offset:47104
	v_add_f32_e32 v166, v166, v111
	v_cvt_pk_bf16_f32 v102, v108, v109
	v_cvt_pk_bf16_f32 v103, v110, v111
	v_exp_f32_e32 v116, v116
	v_exp_f32_e32 v117, v117
	v_exp_f32_e32 v118, v118
	v_exp_f32_e32 v119, v119
	v_add_f32_e32 v141, v141, v112
	v_add_f32_e32 v166, v166, v113
	s_waitcnt lgkmcnt(3)
	v_mfma_f32_32x32x16_bf16 v[64:79], v[176:179], v[186:189], v[64:79]
	v_mfma_f32_32x32x16_bf16 v[80:95], v[180:183], v[186:189], v[80:95]
	ds_read_b128 v[176:179], v155 offset:21664
	ds_read_b128 v[180:183], v155 offset:28320
	ds_read_b128 v[186:189], v135 offset:48128
	v_add_f32_e32 v141, v141, v114
	v_add_f32_e32 v166, v166, v115
	v_cvt_pk_bf16_f32 v104, v112, v113
	v_cvt_pk_bf16_f32 v105, v114, v115
	v_exp_f32_e32 v120, v120
	v_exp_f32_e32 v121, v121
	v_exp_f32_e32 v122, v122
	v_exp_f32_e32 v123, v123
	v_add_f32_e32 v141, v141, v116
	s_waitcnt lgkmcnt(3)
	v_mfma_f32_32x32x16_bf16 v[64:79], v[128:131], v[162:165], v[64:79]
	v_mfma_f32_32x32x16_bf16 v[80:95], v[142:145], v[162:165], v[80:95]
	ds_read_b64_tr_b16 v[128:129], v158 offset:13312
	ds_read_b64_tr_b16 v[130:131], v158 offset:13824
	ds_read_b64_tr_b16 v[142:143], v158 offset:17408
	ds_read_b64_tr_b16 v[144:145], v158 offset:17920
	v_add_f32_e32 v166, v166, v117
	v_add_f32_e32 v141, v141, v118
	v_add_f32_e32 v166, v166, v119
	v_cvt_pk_bf16_f32 v106, v116, v117
	v_cvt_pk_bf16_f32 v107, v118, v119
	v_exp_f32_e32 v124, v124
	v_exp_f32_e32 v125, v125
	v_exp_f32_e32 v126, v126
	v_exp_f32_e32 v127, v127
	s_waitcnt lgkmcnt(4)
; __device__ __forceinline__ void softmax_blk(f32x16& p0, f32x16& p1, f32x16& o0, f32x16& o1, float& mhat, float& lrun, u32x4 (&pf)[4], bool first) {
;     float r0 = max2_(p0[0], p0[1]), r1 = max2_(p1[0], p1[1]);
; #pragma unroll
;     for (int e = 2; e < 16; ++e) { r0 = max2_(r0, p0[e]); r1 = max2_(r1, p1[e]); }
;     const float rm = swap_max(max2_(r0, r1));
;     if (first || __any(rm - mhat > THR)) {
;         const float mn = first ? rm : fmaxf(rm, mhat); const float f = first ? 0.f : __builtin_amdgcn_exp2f(mhat - mn); mhat = mn; lrun *= f;
; #pragma unroll
;         for (int e = 0; e < 16; ++e) { o0[e] *= f; o1[e] *= f; }
;     }
;     float s0 = 0.f, s1 = 0.f;
; #pragma unroll
;     for (int e = 0; e < 16; ++e) { p0[e] = __builtin_amdgcn_exp2f(p0[e] - mhat); p1[e] = __builtin_amdgcn_exp2f(p1[e] - mhat); s0 += p0[e]; s1 += p1[e]; }
;     lrun += s0 + s1;
;     pf[0] = MLA_PACK(p0, 0); pf[1] = MLA_PACK(p0, 8); pf[2] = MLA_PACK(p1, 0); pf[3] = MLA_PACK(p1, 8);
; }
; __device__ __forceinline__ void pv_blk(const u32x4 (&pf)[4], f32x16& o0, f32x16& o1, LAS const unsigned char* vbase) {
; #pragma unroll
;     for (int ks = 0; ks < 4; ++ks) {
;         const bf16x8 p = __builtin_bit_cast(bf16x8, pf[ks]);
;         { const s16x4 lo = vtr(vbase + ks * 1024), hh = vtr(vbase + ks * 1024 + 512); const bf16x8 vf = {lo[0], lo[1], lo[2], lo[3], hh[0], hh[1], hh[2], hh[3]};
;           o0 = __builtin_amdgcn_mfma_f32_32x32x16_bf16(vf, p, o0, 0, 0, 0); }
;         { const s16x4 lo = vtr(vbase + 4096 + ks * 1024), hh = vtr(vbase + 4096 + ks * 1024 + 512); const bf16x8 vf = {lo[0], lo[1], lo[2], lo[3], hh[0], hh[1], hh[2], hh[3]};
;           o1 = __builtin_amdgcn_mfma_f32_32x32x16_bf16(vf, p, o1, 0, 0, 0); }
;     }
; }
; __device__ __forceinline__ void attn_unit(const bf16_t* Qh, const bf16_t* Kh, const bf16_t* Vh, bf16_t* Oh  , int S, int qb, LAS unsigned char* lds, int tid) {
;     ...
;         {
;             f32x16 p0 = {}, p1 = {};
; #pragma unroll
;             for (int s = 0; s < 6; ++s) {
;                 const bf16x8 a0 = *(const LAS bf16x8*)(lds + cur + kfo + s * 32), a1 = *(const LAS bf16x8*)(lds + cur + kfo + 32 * KPITCH + s * 32);
;                 const bf16x8 q = *(const LAS bf16x8*)(ql + (6 + s) * 1024);
;                 p0 = __builtin_amdgcn_mfma_f32_32x32x16_bf16(a0, q, p0, 0, 0, 0); p1 = __builtin_amdgcn_mfma_f32_32x32x16_bf16(a1, q, p1, 0, 0, 0);
	v_mfma_f32_32x32x16_bf16 v[64:79], v[176:179], v[186:189], v[64:79]
	v_mfma_f32_32x32x16_bf16 v[80:95], v[180:183], v[186:189], v[80:95]
	ds_read_b64_tr_b16 v[176:177], v158 offset:14336
	ds_read_b64_tr_b16 v[178:179], v158 offset:14848
	ds_read_b64_tr_b16 v[180:181], v158 offset:18432
	ds_read_b64_tr_b16 v[182:183], v158 offset:18944
	v_add_f32_e32 v141, v141, v120
	v_add_f32_e32 v166, v166, v121
	v_add_f32_e32 v141, v141, v122
	v_add_f32_e32 v166, v166, v123
	v_cvt_pk_bf16_f32 v108, v120, v121
	v_cvt_pk_bf16_f32 v109, v122, v123
	v_add_f32_e32 v141, v141, v124
	v_add_f32_e32 v166, v166, v125
	v_add_f32_e32 v141, v141, v126
	v_add_f32_e32 v166, v166, v127
	v_cvt_pk_bf16_f32 v110, v124, v125
	v_cvt_pk_bf16_f32 v111, v126, v127
	v_add_f32_e32 v141, v141, v166
	s_waitcnt lgkmcnt(4)
	v_mfma_f32_32x32x16_bf16 v[48:63], v[128:131], v[96:99], v[48:63]
	v_mfma_f32_32x32x16_bf16 v[32:47], v[142:145], v[96:99], v[32:47]
	ds_read_b64_tr_b16 v[128:129], v158 offset:15360
	ds_read_b64_tr_b16 v[130:131], v158 offset:15872
	ds_read_b64_tr_b16 v[142:143], v158 offset:19456
	ds_read_b64_tr_b16 v[144:145], v158 offset:19968
	v_max3_f32 v248, v64, v65, v66
	v_max3_f32 v249, v80, v81, v82
	v_max3_f32 v248, v248, v67, v68
	v_max3_f32 v249, v249, v83, v84
	v_max3_f32 v248, v248, v69, v70
	v_max3_f32 v249, v249, v85, v86
	v_max3_f32 v248, v248, v71, v72
	v_max3_f32 v249, v249, v87, v88
	v_max3_f32 v248, v248, v73, v74
	v_max3_f32 v249, v249, v89, v90
	v_max3_f32 v248, v248, v75, v76
	v_max3_f32 v249, v249, v91, v92
	v_max3_f32 v248, v248, v77, v78
	s_waitcnt lgkmcnt(4)
	v_mfma_f32_32x32x16_bf16 v[48:63], v[176:179], v[100:103], v[48:63]
	v_mfma_f32_32x32x16_bf16 v[32:47], v[180:183], v[100:103], v[32:47]
	ds_read_b64_tr_b16 v[176:177], v158 offset:16384
	ds_read_b64_tr_b16 v[178:179], v158 offset:16896
	ds_read_b64_tr_b16 v[180:181], v158 offset:20480
	ds_read_b64_tr_b16 v[182:183], v158 offset:20992
	v_max3_f32 v249, v249, v93, v94
	v_max3_f32 v248, v248, v79, v95
	v_max_f32_e32 v248, v248, v249
	v_cmp_lt_f32_e32 vcc, s72, v248
	s_cbranch_vccnz .Lmla_rescAo
.Lmla_rescAo_back:
	v_exp_f32_e32 v64, v64
	v_exp_f32_e32 v65, v65
	v_exp_f32_e32 v66, v66
	v_exp_f32_e32 v67, v67
	s_waitcnt lgkmcnt(4)
	v_mfma_f32_32x32x16_bf16 v[48:63], v[128:131], v[104:107], v[48:63]
	v_mfma_f32_32x32x16_bf16 v[32:47], v[142:145], v[104:107], v[32:47]
	ds_read_b128 v[128:131], v155 offset:21504
	ds_read_b128 v[142:145], v155 offset:28160
	ds_read_b128 v[162:165], v135 offset:49152
	v_exp_f32_e32 v68, v68
	v_exp_f32_e32 v69, v69
	v_exp_f32_e32 v70, v70
	v_exp_f32_e32 v71, v71
	v_add_f32_e32 v166, v64, v65
	v_add_f32_e32 v140, v140, v66
	v_add_f32_e32 v166, v166, v67
	v_cvt_pk_bf16_f32 v64, v64, v65
	v_cvt_pk_bf16_f32 v65, v66, v67
	s_waitcnt lgkmcnt(3)
	v_mfma_f32_32x32x16_bf16 v[48:63], v[176:179], v[108:111], v[48:63]
	v_mfma_f32_32x32x16_bf16 v[32:47], v[180:183], v[108:111], v[32:47]
	ds_read_b128 v[176:179], v155 offset:21536
	ds_read_b128 v[180:183], v155 offset:28192
	ds_read_b128 v[186:189], v135 offset:50176
	v_exp_f32_e32 v72, v72
	v_exp_f32_e32 v73, v73
	v_exp_f32_e32 v74, v74
	v_exp_f32_e32 v75, v75
	v_add_f32_e32 v140, v140, v68
	v_add_f32_e32 v166, v166, v69
	v_add_f32_e32 v140, v140, v70
	v_add_f32_e32 v166, v166, v71
	v_cvt_pk_bf16_f32 v66, v68, v69
	s_waitcnt lgkmcnt(3)
	v_mfma_f32_32x32x16_bf16 v[96:111], v[128:131], v[162:165], v[190:205]
	v_mfma_f32_32x32x16_bf16 v[112:127], v[142:145], v[162:165], v[190:205]
	ds_read_b128 v[128:131], v155 offset:21568
	ds_read_b128 v[142:145], v155 offset:28224
	ds_read_b128 v[162:165], v135 offset:51200
	v_cvt_pk_bf16_f32 v67, v70, v71
	v_exp_f32_e32 v76, v76
	v_exp_f32_e32 v77, v77
	v_exp_f32_e32 v78, v78
	v_exp_f32_e32 v79, v79
	v_add_f32_e32 v140, v140, v72
	v_add_f32_e32 v166, v166, v73
	v_add_f32_e32 v140, v140, v74
	v_add_f32_e32 v166, v166, v75
	s_waitcnt lgkmcnt(3)
	v_mfma_f32_32x32x16_bf16 v[96:111], v[176:179], v[186:189], v[96:111]
	v_mfma_f32_32x32x16_bf16 v[112:127], v[180:183], v[186:189], v[112:127]
	ds_read_b128 v[176:179], v155 offset:21600
	ds_read_b128 v[180:183], v155 offset:28256
	ds_read_b128 v[186:189], v135 offset:52224
	v_cvt_pk_bf16_f32 v68, v72, v73
	v_cvt_pk_bf16_f32 v69, v74, v75
	v_exp_f32_e32 v80, v80
	v_exp_f32_e32 v81, v81
	v_exp_f32_e32 v82, v82
	v_exp_f32_e32 v83, v83
	v_add_f32_e32 v140, v140, v76
	v_add_f32_e32 v166, v166, v77
	v_add_f32_e32 v140, v140, v78
	s_waitcnt lgkmcnt(3)
	v_mfma_f32_32x32x16_bf16 v[96:111], v[128:131], v[162:165], v[96:111]
	v_mfma_f32_32x32x16_bf16 v[112:127], v[142:145], v[162:165], v[112:127]
	ds_read_b128 v[128:131], v155 offset:21632
	ds_read_b128 v[142:145], v155 offset:28288
	ds_read_b128 v[162:165], v135 offset:53248
	v_add_f32_e32 v166, v166, v79
	v_cvt_pk_bf16_f32 v70, v76, v77
	v_cvt_pk_bf16_f32 v71, v78, v79
	v_exp_f32_e32 v84, v84
	v_exp_f32_e32 v85, v85
	v_exp_f32_e32 v86, v86
	v_exp_f32_e32 v87, v87
	v_add_f32_e32 v140, v140, v80
	v_add_f32_e32 v166, v166, v81
	s_waitcnt lgkmcnt(3)
	v_mfma_f32_32x32x16_bf16 v[96:111], v[176:179], v[186:189], v[96:111]
	v_mfma_f32_32x32x16_bf16 v[112:127], v[180:183], v[186:189], v[112:127]
	ds_read_b128 v[176:179], v155 offset:21664
	ds_read_b128 v[180:183], v155 offset:28320
	ds_read_b128 v[186:189], v135 offset:54272
	v_add_f32_e32 v140, v140, v82
	v_add_f32_e32 v166, v166, v83
	v_cvt_pk_bf16_f32 v72, v80, v81
	v_cvt_pk_bf16_f32 v73, v82, v83
	v_exp_f32_e32 v88, v88
	v_exp_f32_e32 v89, v89
	v_exp_f32_e32 v90, v90
	v_exp_f32_e32 v91, v91
	v_add_f32_e32 v140, v140, v84
	s_waitcnt vmcnt(0)
	ds_write_b128 v150, v[218:221]
	ds_write_b128 v156, v[222:225]
	ds_write_b128 v157, v[226:229] offset:34816
	s_waitcnt lgkmcnt(6)
	v_mfma_f32_32x32x16_bf16 v[96:111], v[128:131], v[162:165], v[96:111]
	v_mfma_f32_32x32x16_bf16 v[112:127], v[142:145], v[162:165], v[112:127]
	v_add_f32_e32 v166, v166, v85
	v_add_f32_e32 v140, v140, v86
	v_add_f32_e32 v166, v166, v87
	v_cvt_pk_bf16_f32 v74, v84, v85
	v_cvt_pk_bf16_f32 v75, v86, v87
	v_exp_f32_e32 v92, v92
	v_exp_f32_e32 v93, v93
	v_exp_f32_e32 v94, v94
	v_exp_f32_e32 v95, v95
	s_waitcnt lgkmcnt(3)
	v_mfma_f32_32x32x16_bf16 v[96:111], v[176:179], v[186:189], v[96:111]
	v_mfma_f32_32x32x16_bf16 v[112:127], v[180:183], v[186:189], v[112:127]
	v_add_f32_e32 v140, v140, v88
	v_add_f32_e32 v166, v166, v89
	v_add_f32_e32 v140, v140, v90
	v_add_f32_e32 v166, v166, v91
	v_cvt_pk_bf16_f32 v76, v88, v89
	v_cvt_pk_bf16_f32 v77, v90, v91
	v_add_f32_e32 v140, v140, v92
	v_add_f32_e32 v166, v166, v93
	v_add_f32_e32 v140, v140, v94
	v_add_f32_e32 v166, v166, v95
	v_cvt_pk_bf16_f32 v78, v92, v93
	v_cvt_pk_bf16_f32 v79, v94, v95
	v_add_f32_e32 v140, v140, v166
	s_waitcnt lgkmcnt(0)
	s_barrier
; #define LAS __attribute__((address_space(3)))
; __device__ __forceinline__ float max2_(float a, float b) { return __builtin_amdgcn_fmed3f(a, b, INFINITY); }
; __device__ __forceinline__ void softmax_blk(f32x16& p0, f32x16& p1, f32x16& o0, f32x16& o1, float& mhat, float& lrun, u32x4 (&pf)[4], bool first) {
;     float r0 = max2_(p0[0], p0[1]), r1 = max2_(p1[0], p1[1]);
; #pragma unroll
;     for (int e = 2; e < 16; ++e) { r0 = max2_(r0, p0[e]); r1 = max2_(r1, p1[e]); }
;     const float rm = swap_max(max2_(r0, r1));
;     if (first || __any(rm - mhat > THR)) {
;         const float mn = first ? rm : fmaxf(rm, mhat); const float f = first ? 0.f : __builtin_amdgcn_exp2f(mhat - mn); mhat = mn; lrun *= f;
; #pragma unroll
;         for (int e = 0; e < 16; ++e) { o0[e] *= f; o1[e] *= f; }
;     }
;     float s0 = 0.f, s1 = 0.f;
; #pragma unroll
;     for (int e = 0; e < 16; ++e) { p0[e] = __builtin_amdgcn_exp2f(p0[e] - mhat); p1[e] = __builtin_amdgcn_exp2f(p1[e] - mhat); s0 += p0[e]; s1 += p1[e]; }
;     lrun += s0 + s1;
;     pf[0] = MLA_PACK(p0, 0); pf[1] = MLA_PACK(p0, 8); pf[2] = MLA_PACK(p1, 0); pf[3] = MLA_PACK(p1, 8);
; }
; __device__ __forceinline__ void pv_blk(const u32x4 (&pf)[4], f32x16& o0, f32x16& o1, LAS const unsigned char* vbase) {
; #pragma unroll
;     for (int ks = 0; ks < 4; ++ks) {
;         const bf16x8 p = __builtin_bit_cast(bf16x8, pf[ks]);
;         { const s16x4 lo = vtr(vbase + ks * 1024), hh = vtr(vbase + ks * 1024 + 512); const bf16x8 vf = {lo[0], lo[1], lo[2], lo[3], hh[0], hh[1], hh[2], hh[3]};
;           o0 = __builtin_amdgcn_mfma_f32_32x32x16_bf16(vf, p, o0, 0, 0, 0); }
;         { const s16x4 lo = vtr(vbase + 4096 + ks * 1024), hh = vtr(vbase + 4096 + ks * 1024 + 512); const bf16x8 vf = {lo[0], lo[1], lo[2], lo[3], hh[0], hh[1], hh[2], hh[3]};
;           o1 = __builtin_amdgcn_mfma_f32_32x32x16_bf16(vf, p, o1, 0, 0, 0); }
;     }
; }
; __device__ __forceinline__ void attn_unit(const bf16_t* Qh, const bf16_t* Kh, const bf16_t* Vh, bf16_t* Oh  , int S, int qb, LAS unsigned char* lds, int tid) {
;     ...
;     for (int t = 0; t < NT; ++t) {
;         const unsigned cur = (unsigned)(t & 1) * BUF, nxt = BUF - cur;
;         const int tn = t + 1 < NT ? t + 1 : t;
;         ka = GLD(u32x4, Kg + (size_t)tn * 768 + kc0); kb = GLD(u32x4, Kg + (size_t)tn * 768 + kc1); va = GLD(u32x4, Vg + (size_t)tn * 512 + tid);
	s_add_i32 s1, s1, 1
	s_cmp_lg_u32 s1, s18
	s_cbranch_scc0 .Lmla_epi
	ds_read_b64_tr_b16 v[128:129], v158 offset:34816
	ds_read_b64_tr_b16 v[130:131], v158 offset:35328
	ds_read_b64_tr_b16 v[142:143], v158 offset:38912
	ds_read_b64_tr_b16 v[144:145], v158 offset:39424
	ds_read_b64_tr_b16 v[176:177], v158 offset:35840
	ds_read_b64_tr_b16 v[178:179], v158 offset:36352
	ds_read_b64_tr_b16 v[180:181], v158 offset:39936
	ds_read_b64_tr_b16 v[182:183], v158 offset:40448
	s_waitcnt lgkmcnt(4)
	v_mfma_f32_32x32x16_bf16 v[16:31], v[128:131], v[64:67], v[16:31]
	v_mfma_f32_32x32x16_bf16 v[0:15], v[142:145], v[64:67], v[0:15]
	ds_read_b64_tr_b16 v[128:129], v158 offset:36864
	ds_read_b64_tr_b16 v[130:131], v158 offset:37376
	ds_read_b64_tr_b16 v[142:143], v158 offset:40960
	ds_read_b64_tr_b16 v[144:145], v158 offset:41472
	global_load_dwordx4 v[218:221], v171, s[26:27]
	s_cmp_eq_u64 s[36:37], 0
	s_cbranch_scc1 .Lmla_nok1Ae
	global_load_dwordx4 v[222:225], v184, s[26:27]
.Lmla_nok1Ae:
	global_load_dwordx4 v[226:229], v146, s[100:101]
	s_add_u32 s26, s26, 0x3000
	s_addc_u32 s27, s27, 0
	s_add_u32 s100, s100, 0x2000
	s_addc_u32 s101, s101, 0
	v_max3_f32 v248, v96, v97, v98
	v_max3_f32 v249, v112, v113, v114
	v_max3_f32 v248, v248, v99, v100
	v_max3_f32 v249, v249, v115, v116
	v_max3_f32 v248, v248, v101, v102
	v_max3_f32 v249, v249, v117, v118
	v_max3_f32 v248, v248, v103, v104
	v_max3_f32 v249, v249, v119, v120
	v_max3_f32 v248, v248, v105, v106
	v_max3_f32 v249, v249, v121, v122
	v_max3_f32 v248, v248, v107, v108
	v_max3_f32 v249, v249, v123, v124
	v_max3_f32 v248, v248, v109, v110
	s_waitcnt lgkmcnt(4)
	v_mfma_f32_32x32x16_bf16 v[16:31], v[176:179], v[68:71], v[16:31]
	v_mfma_f32_32x32x16_bf16 v[0:15], v[180:183], v[68:71], v[0:15]
	ds_read_b64_tr_b16 v[176:177], v158 offset:37888
	ds_read_b64_tr_b16 v[178:179], v158 offset:38400
	ds_read_b64_tr_b16 v[180:181], v158 offset:41984
	ds_read_b64_tr_b16 v[182:183], v158 offset:42496
	v_max3_f32 v249, v249, v125, v126
	v_max3_f32 v248, v248, v111, v127
	v_max_f32_e32 v248, v248, v249
	v_cmp_lt_f32_e32 vcc, s72, v248
	s_cbranch_vccnz .Lmla_rescBv
.Lmla_rescBv_back:
	v_exp_f32_e32 v96, v96
	v_exp_f32_e32 v97, v97
	v_exp_f32_e32 v98, v98
	v_exp_f32_e32 v99, v99
	s_waitcnt lgkmcnt(4)
	v_mfma_f32_32x32x16_bf16 v[16:31], v[128:131], v[72:75], v[16:31]
	v_mfma_f32_32x32x16_bf16 v[0:15], v[142:145], v[72:75], v[0:15]
	ds_read_b128 v[128:131], v155
	ds_read_b128 v[142:145], v155 offset:6656
	ds_read_b128 v[162:165], v135 offset:43008
	v_exp_f32_e32 v100, v100
	v_exp_f32_e32 v101, v101
	v_exp_f32_e32 v102, v102
	v_exp_f32_e32 v103, v103
	v_add_f32_e32 v166, v96, v97
	v_add_f32_e32 v141, v141, v98
	v_add_f32_e32 v166, v166, v99
	v_cvt_pk_bf16_f32 v96, v96, v97
	v_cvt_pk_bf16_f32 v97, v98, v99
	s_waitcnt lgkmcnt(3)
	v_mfma_f32_32x32x16_bf16 v[16:31], v[176:179], v[76:79], v[16:31]
	v_mfma_f32_32x32x16_bf16 v[0:15], v[180:183], v[76:79], v[0:15]
	ds_read_b128 v[176:179], v155 offset:32
	ds_read_b128 v[180:183], v155 offset:6688
	ds_read_b128 v[186:189], v135 offset:44032
	v_exp_f32_e32 v104, v104
	v_exp_f32_e32 v105, v105
	v_exp_f32_e32 v106, v106
	v_exp_f32_e32 v107, v107
	v_add_f32_e32 v141, v141, v100
	v_add_f32_e32 v166, v166, v101
	v_add_f32_e32 v141, v141, v102
	v_add_f32_e32 v166, v166, v103
	v_cvt_pk_bf16_f32 v98, v100, v101
	s_waitcnt lgkmcnt(3)
	v_mfma_f32_32x32x16_bf16 v[64:79], v[128:131], v[162:165], v[232:247]
	v_mfma_f32_32x32x16_bf16 v[80:95], v[142:145], v[162:165], v[232:247]
	ds_read_b128 v[128:131], v155 offset:64
	ds_read_b128 v[142:145], v155 offset:6720
	ds_read_b128 v[162:165], v135 offset:45056
	v_cvt_pk_bf16_f32 v99, v102, v103
	v_exp_f32_e32 v108, v108
	v_exp_f32_e32 v109, v109
	v_exp_f32_e32 v110, v110
	v_exp_f32_e32 v111, v111
	v_add_f32_e32 v141, v141, v104
	v_add_f32_e32 v166, v166, v105
	v_add_f32_e32 v141, v141, v106
	v_add_f32_e32 v166, v166, v107
	s_waitcnt lgkmcnt(3)
	v_mfma_f32_32x32x16_bf16 v[64:79], v[176:179], v[186:189], v[64:79]
	v_mfma_f32_32x32x16_bf16 v[80:95], v[180:183], v[186:189], v[80:95]
	ds_read_b128 v[176:179], v155 offset:96
	ds_read_b128 v[180:183], v155 offset:6752
	ds_read_b128 v[186:189], v135 offset:46080
	v_cvt_pk_bf16_f32 v100, v104, v105
	v_cvt_pk_bf16_f32 v101, v106, v107
	v_exp_f32_e32 v112, v112
	v_exp_f32_e32 v113, v113
	v_exp_f32_e32 v114, v114
	v_exp_f32_e32 v115, v115
	v_add_f32_e32 v141, v141, v108
	v_add_f32_e32 v166, v166, v109
	v_add_f32_e32 v141, v141, v110
	s_waitcnt lgkmcnt(3)
	v_mfma_f32_32x32x16_bf16 v[64:79], v[128:131], v[162:165], v[64:79]
	v_mfma_f32_32x32x16_bf16 v[80:95], v[142:145], v[162:165], v[80:95]
	ds_read_b128 v[128:131], v155 offset:128
	ds_read_b128 v[142:145], v155 offset:6784
	ds_read_b128 v[162:165], v135 offset:47104
	v_add_f32_e32 v166, v166, v111
	v_cvt_pk_bf16_f32 v102, v108, v109
	v_cvt_pk_bf16_f32 v103, v110, v111
	v_exp_f32_e32 v116, v116
	v_exp_f32_e32 v117, v117
	v_exp_f32_e32 v118, v118
	v_exp_f32_e32 v119, v119
	v_add_f32_e32 v141, v141, v112
	v_add_f32_e32 v166, v166, v113
	s_waitcnt lgkmcnt(3)
	v_mfma_f32_32x32x16_bf16 v[64:79], v[176:179], v[186:189], v[64:79]
	v_mfma_f32_32x32x16_bf16 v[80:95], v[180:183], v[186:189], v[80:95]
	ds_read_b128 v[176:179], v155 offset:160
	ds_read_b128 v[180:183], v155 offset:6816
	ds_read_b128 v[186:189], v135 offset:48128
	v_add_f32_e32 v141, v141, v114
	v_add_f32_e32 v166, v166, v115
	v_cvt_pk_bf16_f32 v104, v112, v113
	v_cvt_pk_bf16_f32 v105, v114, v115
	v_exp_f32_e32 v120, v120
	v_exp_f32_e32 v121, v121
	v_exp_f32_e32 v122, v122
	v_exp_f32_e32 v123, v123
	v_add_f32_e32 v141, v141, v116
	s_waitcnt lgkmcnt(3)
; #define LAS __attribute__((address_space(3)))
; __device__ __forceinline__ float swap_max(float m) { auto rr = __builtin_amdgcn_permlane32_swap(__float_as_uint(m), __float_as_uint(m), false, false); return fmaxf(__uint_as_float(rr[0]), __uint_as_float(rr[1])); }
; __device__ __forceinline__ s16x4 vtr(LAS const unsigned char* p) { return __builtin_bit_cast(s16x4, __builtin_amdgcn_ds_read_tr16_b64_v4i16((LAS s16x4*)p)); }
; #define MLA_PACK(P, b) (u32x4){cvt_pk_bf16(P[b], P[b + 1]), cvt_pk_bf16(P[b + 2], P[b + 3]), cvt_pk_bf16(P[b + 4], P[b + 5]), cvt_pk_bf16(P[b + 6], P[b + 7])}
; __device__ __forceinline__ void softmax_blk(f32x16& p0, f32x16& p1, f32x16& o0, f32x16& o1, float& mhat, float& lrun, u32x4 (&pf)[4], bool first) {
;     float r0 = max2_(p0[0], p0[1]), r1 = max2_(p1[0], p1[1]);
; #pragma unroll
;     for (int e = 2; e < 16; ++e) { r0 = max2_(r0, p0[e]); r1 = max2_(r1, p1[e]); }
;     const float rm = swap_max(max2_(r0, r1));
;     if (first || __any(rm - mhat > THR)) {
;         const float mn = first ? rm : fmaxf(rm, mhat); const float f = first ? 0.f : __builtin_amdgcn_exp2f(mhat - mn); mhat = mn; lrun *= f;
; #pragma unroll
;         for (int e = 0; e < 16; ++e) { o0[e] *= f; o1[e] *= f; }
;     }
;     float s0 = 0.f, s1 = 0.f;
; #pragma unroll
;     for (int e = 0; e < 16; ++e) { p0[e] = __builtin_amdgcn_exp2f(p0[e] - mhat); p1[e] = __builtin_amdgcn_exp2f(p1[e] - mhat); s0 += p0[e]; s1 += p1[e]; }
;     lrun += s0 + s1;
;     pf[0] = MLA_PACK(p0, 0); pf[1] = MLA_PACK(p0, 8); pf[2] = MLA_PACK(p1, 0); pf[3] = MLA_PACK(p1, 8);
; }
; __device__ __forceinline__ void pv_blk(const u32x4 (&pf)[4], f32x16& o0, f32x16& o1, LAS const unsigned char* vbase) {
; #pragma unroll
;     for (int ks = 0; ks < 4; ++ks) {
;         const bf16x8 p = __builtin_bit_cast(bf16x8, pf[ks]);
;         { const s16x4 lo = vtr(vbase + ks * 1024), hh = vtr(vbase + ks * 1024 + 512); const bf16x8 vf = {lo[0], lo[1], lo[2], lo[3], hh[0], hh[1], hh[2], hh[3]};
;           o0 = __builtin_amdgcn_mfma_f32_32x32x16_bf16(vf, p, o0, 0, 0, 0); }
;         { const s16x4 lo = vtr(vbase + 4096 + ks * 1024), hh = vtr(vbase + 4096 + ks * 1024 + 512); const bf16x8 vf = {lo[0], lo[1], lo[2], lo[3], hh[0], hh[1], hh[2], hh[3]};
;           o1 = __builtin_amdgcn_mfma_f32_32x32x16_bf16(vf, p, o1, 0, 0, 0); }
;     }
; }
	v_mfma_f32_32x32x16_bf16 v[64:79], v[128:131], v[162:165], v[64:79]
	v_mfma_f32_32x32x16_bf16 v[80:95], v[142:145], v[162:165], v[80:95]
	ds_read_b64_tr_b16 v[128:129], v158 offset:34816
	ds_read_b64_tr_b16 v[130:131], v158 offset:35328
	ds_read_b64_tr_b16 v[142:143], v158 offset:38912
	ds_read_b64_tr_b16 v[144:145], v158 offset:39424
	v_add_f32_e32 v166, v166, v117
	v_add_f32_e32 v141, v141, v118
	v_add_f32_e32 v166, v166, v119
	v_cvt_pk_bf16_f32 v106, v116, v117
	v_cvt_pk_bf16_f32 v107, v118, v119
	v_exp_f32_e32 v124, v124
	v_exp_f32_e32 v125, v125
	v_exp_f32_e32 v126, v126
	v_exp_f32_e32 v127, v127
	s_waitcnt lgkmcnt(4)
	v_mfma_f32_32x32x16_bf16 v[64:79], v[176:179], v[186:189], v[64:79]
	v_mfma_f32_32x32x16_bf16 v[80:95], v[180:183], v[186:189], v[80:95]
	ds_read_b64_tr_b16 v[176:177], v158 offset:35840
	ds_read_b64_tr_b16 v[178:179], v158 offset:36352
	ds_read_b64_tr_b16 v[180:181], v158 offset:39936
	ds_read_b64_tr_b16 v[182:183], v158 offset:40448
	v_add_f32_e32 v141, v141, v120
	v_add_f32_e32 v166, v166, v121
	v_add_f32_e32 v141, v141, v122
	v_add_f32_e32 v166, v166, v123
	v_cvt_pk_bf16_f32 v108, v120, v121
	v_cvt_pk_bf16_f32 v109, v122, v123
	v_add_f32_e32 v141, v141, v124
	v_add_f32_e32 v166, v166, v125
	v_add_f32_e32 v141, v141, v126
	v_add_f32_e32 v166, v166, v127
	v_cvt_pk_bf16_f32 v110, v124, v125
	v_cvt_pk_bf16_f32 v111, v126, v127
	v_add_f32_e32 v141, v141, v166
	s_waitcnt lgkmcnt(4)
	v_mfma_f32_32x32x16_bf16 v[48:63], v[128:131], v[96:99], v[48:63]
	v_mfma_f32_32x32x16_bf16 v[32:47], v[142:145], v[96:99], v[32:47]
	ds_read_b64_tr_b16 v[128:129], v158 offset:36864
	ds_read_b64_tr_b16 v[130:131], v158 offset:37376
	ds_read_b64_tr_b16 v[142:143], v158 offset:40960
	ds_read_b64_tr_b16 v[144:145], v158 offset:41472
	v_max3_f32 v248, v64, v65, v66
	v_max3_f32 v249, v80, v81, v82
	v_max3_f32 v248, v248, v67, v68
	v_max3_f32 v249, v249, v83, v84
	v_max3_f32 v248, v248, v69, v70
	v_max3_f32 v249, v249, v85, v86
	v_max3_f32 v248, v248, v71, v72
	v_max3_f32 v249, v249, v87, v88
	v_max3_f32 v248, v248, v73, v74
	v_max3_f32 v249, v249, v89, v90
	v_max3_f32 v248, v248, v75, v76
	v_max3_f32 v249, v249, v91, v92
	v_max3_f32 v248, v248, v77, v78
	s_waitcnt lgkmcnt(4)
	v_mfma_f32_32x32x16_bf16 v[48:63], v[176:179], v[100:103], v[48:63]
	v_mfma_f32_32x32x16_bf16 v[32:47], v[180:183], v[100:103], v[32:47]
	ds_read_b64_tr_b16 v[176:177], v158 offset:37888
	ds_read_b64_tr_b16 v[178:179], v158 offset:38400
	ds_read_b64_tr_b16 v[180:181], v158 offset:41984
	ds_read_b64_tr_b16 v[182:183], v158 offset:42496
	v_max3_f32 v249, v249, v93, v94
	v_max3_f32 v248, v248, v79, v95
	v_max_f32_e32 v248, v248, v249
	v_cmp_lt_f32_e32 vcc, s72, v248
	s_cbranch_vccnz .Lmla_rescAe
; #define LAS __attribute__((address_space(3)))
; __device__ __forceinline__ void softmax_blk(f32x16& p0, f32x16& p1, f32x16& o0, f32x16& o1, float& mhat, float& lrun, u32x4 (&pf)[4], bool first) {
;     float r0 = max2_(p0[0], p0[1]), r1 = max2_(p1[0], p1[1]);
; #pragma unroll
;     for (int e = 2; e < 16; ++e) { r0 = max2_(r0, p0[e]); r1 = max2_(r1, p1[e]); }
;     const float rm = swap_max(max2_(r0, r1));
;     if (first || __any(rm - mhat > THR)) {
;         const float mn = first ? rm : fmaxf(rm, mhat); const float f = first ? 0.f : __builtin_amdgcn_exp2f(mhat - mn); mhat = mn; lrun *= f;
; #pragma unroll
;         for (int e = 0; e < 16; ++e) { o0[e] *= f; o1[e] *= f; }
;     }
;     float s0 = 0.f, s1 = 0.f;
; #pragma unroll
;     for (int e = 0; e < 16; ++e) { p0[e] = __builtin_amdgcn_exp2f(p0[e] - mhat); p1[e] = __builtin_amdgcn_exp2f(p1[e] - mhat); s0 += p0[e]; s1 += p1[e]; }
;     lrun += s0 + s1;
;     pf[0] = MLA_PACK(p0, 0); pf[1] = MLA_PACK(p0, 8); pf[2] = MLA_PACK(p1, 0); pf[3] = MLA_PACK(p1, 8);
; }
; __device__ __forceinline__ void pv_blk(const u32x4 (&pf)[4], f32x16& o0, f32x16& o1, LAS const unsigned char* vbase) {
; #pragma unroll
;     for (int ks = 0; ks < 4; ++ks) {
;         const bf16x8 p = __builtin_bit_cast(bf16x8, pf[ks]);
;         { const s16x4 lo = vtr(vbase + ks * 1024), hh = vtr(vbase + ks * 1024 + 512); const bf16x8 vf = {lo[0], lo[1], lo[2], lo[3], hh[0], hh[1], hh[2], hh[3]};
;           o0 = __builtin_amdgcn_mfma_f32_32x32x16_bf16(vf, p, o0, 0, 0, 0); }
;         { const s16x4 lo = vtr(vbase + 4096 + ks * 1024), hh = vtr(vbase + 4096 + ks * 1024 + 512); const bf16x8 vf = {lo[0], lo[1], lo[2], lo[3], hh[0], hh[1], hh[2], hh[3]};
;           o1 = __builtin_amdgcn_mfma_f32_32x32x16_bf16(vf, p, o1, 0, 0, 0); }
;     }
; }
; __device__ __forceinline__ void attn_unit(const bf16_t* Qh, const bf16_t* Kh, const bf16_t* Vh, bf16_t* Oh  , int S, int qb, LAS unsigned char* lds, int tid) {
;     ...
;             for (int s = 0; s < 6; ++s) {
;                 const bf16x8 a0 = *(const LAS bf16x8*)(lds + cur + kfo + s * 32), a1 = *(const LAS bf16x8*)(lds + cur + kfo + 32 * KPITCH + s * 32);
;                 const bf16x8 q = *(const LAS bf16x8*)(ql + (6 + s) * 1024);
;                 p0 = __builtin_amdgcn_mfma_f32_32x32x16_bf16(a0, q, p0, 0, 0, 0); p1 = __builtin_amdgcn_mfma_f32_32x32x16_bf16(a1, q, p1, 0, 0, 0);
;             }
.Lmla_rescAe_back:
	v_exp_f32_e32 v64, v64
	v_exp_f32_e32 v65, v65
	v_exp_f32_e32 v66, v66
	v_exp_f32_e32 v67, v67
	s_waitcnt lgkmcnt(4)
	v_mfma_f32_32x32x16_bf16 v[48:63], v[128:131], v[104:107], v[48:63]
	v_mfma_f32_32x32x16_bf16 v[32:47], v[142:145], v[104:107], v[32:47]
	ds_read_b128 v[128:131], v155
	ds_read_b128 v[142:145], v155 offset:6656
	ds_read_b128 v[162:165], v135 offset:49152
	v_exp_f32_e32 v68, v68
	v_exp_f32_e32 v69, v69
	v_exp_f32_e32 v70, v70
	v_exp_f32_e32 v71, v71
	v_add_f32_e32 v166, v64, v65
	v_add_f32_e32 v140, v140, v66
	v_add_f32_e32 v166, v166, v67
	v_cvt_pk_bf16_f32 v64, v64, v65
	v_cvt_pk_bf16_f32 v65, v66, v67
	s_waitcnt lgkmcnt(3)
	v_mfma_f32_32x32x16_bf16 v[48:63], v[176:179], v[108:111], v[48:63]
	v_mfma_f32_32x32x16_bf16 v[32:47], v[180:183], v[108:111], v[32:47]
	ds_read_b128 v[176:179], v155 offset:32
	ds_read_b128 v[180:183], v155 offset:6688
	ds_read_b128 v[186:189], v135 offset:50176
	v_exp_f32_e32 v72, v72
	v_exp_f32_e32 v73, v73
	v_exp_f32_e32 v74, v74
	v_exp_f32_e32 v75, v75
	v_add_f32_e32 v140, v140, v68
	v_add_f32_e32 v166, v166, v69
	v_add_f32_e32 v140, v140, v70
	v_add_f32_e32 v166, v166, v71
	v_cvt_pk_bf16_f32 v66, v68, v69
	s_waitcnt lgkmcnt(3)
	v_mfma_f32_32x32x16_bf16 v[96:111], v[128:131], v[162:165], v[190:205]
	v_mfma_f32_32x32x16_bf16 v[112:127], v[142:145], v[162:165], v[190:205]
	ds_read_b128 v[128:131], v155 offset:64
	ds_read_b128 v[142:145], v155 offset:6720
	ds_read_b128 v[162:165], v135 offset:51200
	v_cvt_pk_bf16_f32 v67, v70, v71
	v_exp_f32_e32 v76, v76
	v_exp_f32_e32 v77, v77
	v_exp_f32_e32 v78, v78
	v_exp_f32_e32 v79, v79
	v_add_f32_e32 v140, v140, v72
	v_add_f32_e32 v166, v166, v73
	v_add_f32_e32 v140, v140, v74
	v_add_f32_e32 v166, v166, v75
	s_waitcnt lgkmcnt(3)
	v_mfma_f32_32x32x16_bf16 v[96:111], v[176:179], v[186:189], v[96:111]
	v_mfma_f32_32x32x16_bf16 v[112:127], v[180:183], v[186:189], v[112:127]
	ds_read_b128 v[176:179], v155 offset:96
	ds_read_b128 v[180:183], v155 offset:6752
	ds_read_b128 v[186:189], v135 offset:52224
	v_cvt_pk_bf16_f32 v68, v72, v73
	v_cvt_pk_bf16_f32 v69, v74, v75
	v_exp_f32_e32 v80, v80
	v_exp_f32_e32 v81, v81
	v_exp_f32_e32 v82, v82
	v_exp_f32_e32 v83, v83
	v_add_f32_e32 v140, v140, v76
	v_add_f32_e32 v166, v166, v77
	v_add_f32_e32 v140, v140, v78
	s_waitcnt lgkmcnt(3)
	v_mfma_f32_32x32x16_bf16 v[96:111], v[128:131], v[162:165], v[96:111]
	v_mfma_f32_32x32x16_bf16 v[112:127], v[142:145], v[162:165], v[112:127]
	ds_read_b128 v[128:131], v155 offset:128
	ds_read_b128 v[142:145], v155 offset:6784
	ds_read_b128 v[162:165], v135 offset:53248
	v_add_f32_e32 v166, v166, v79
	v_cvt_pk_bf16_f32 v70, v76, v77
	v_cvt_pk_bf16_f32 v71, v78, v79
	v_exp_f32_e32 v84, v84
	v_exp_f32_e32 v85, v85
	v_exp_f32_e32 v86, v86
	v_exp_f32_e32 v87, v87
	v_add_f32_e32 v140, v140, v80
	v_add_f32_e32 v166, v166, v81
	s_waitcnt lgkmcnt(3)
	v_mfma_f32_32x32x16_bf16 v[96:111], v[176:179], v[186:189], v[96:111]
	v_mfma_f32_32x32x16_bf16 v[112:127], v[180:183], v[186:189], v[112:127]
	ds_read_b128 v[176:179], v155 offset:160
	ds_read_b128 v[180:183], v155 offset:6816
	ds_read_b128 v[186:189], v135 offset:54272
	v_add_f32_e32 v140, v140, v82
	v_add_f32_e32 v166, v166, v83
	v_cvt_pk_bf16_f32 v72, v80, v81
	v_cvt_pk_bf16_f32 v73, v82, v83
	v_exp_f32_e32 v88, v88
	v_exp_f32_e32 v89, v89
	v_exp_f32_e32 v90, v90
	v_exp_f32_e32 v91, v91
	v_add_f32_e32 v140, v140, v84
	s_waitcnt vmcnt(0)
	ds_write_b128 v150, v[218:221] offset:21504
	ds_write_b128 v159, v[222:225]
	ds_write_b128 v157, v[226:229] offset:13312
	s_waitcnt lgkmcnt(6)
	v_mfma_f32_32x32x16_bf16 v[96:111], v[128:131], v[162:165], v[96:111]
	v_mfma_f32_32x32x16_bf16 v[112:127], v[142:145], v[162:165], v[112:127]
	v_add_f32_e32 v166, v166, v85
	v_add_f32_e32 v140, v140, v86
	v_add_f32_e32 v166, v166, v87
	v_cvt_pk_bf16_f32 v74, v84, v85
	v_cvt_pk_bf16_f32 v75, v86, v87
	v_exp_f32_e32 v92, v92
	v_exp_f32_e32 v93, v93
	v_exp_f32_e32 v94, v94
	v_exp_f32_e32 v95, v95
	s_waitcnt lgkmcnt(3)
	v_mfma_f32_32x32x16_bf16 v[96:111], v[176:179], v[186:189], v[96:111]
	v_mfma_f32_32x32x16_bf16 v[112:127], v[180:183], v[186:189], v[112:127]
	v_add_f32_e32 v140, v140, v88
	v_add_f32_e32 v166, v166, v89
	v_add_f32_e32 v140, v140, v90
	v_add_f32_e32 v166, v166, v91
	v_cvt_pk_bf16_f32 v76, v88, v89
	v_cvt_pk_bf16_f32 v77, v90, v91
	v_add_f32_e32 v140, v140, v92
	v_add_f32_e32 v166, v166, v93
	v_add_f32_e32 v140, v140, v94
	v_add_f32_e32 v166, v166, v95
	v_cvt_pk_bf16_f32 v78, v92, v93
	v_cvt_pk_bf16_f32 v79, v94, v95
	v_add_f32_e32 v140, v140, v166
	s_waitcnt lgkmcnt(0)
	s_barrier
	s_add_i32 s1, s1, 1
	s_branch .Lmla_top

; #define LAS __attribute__((address_space(3)))
; __device__ __forceinline__ s16x4 vtr(LAS const unsigned char* p) { return __builtin_bit_cast(s16x4, __builtin_amdgcn_ds_read_tr16_b64_v4i16((LAS s16x4*)p)); }
; #define MLA_PACK(P, b) (u32x4){cvt_pk_bf16(P[b], P[b + 1]), cvt_pk_bf16(P[b + 2], P[b + 3]), cvt_pk_bf16(P[b + 4], P[b + 5]), cvt_pk_bf16(P[b + 6], P[b + 7])}
; __device__ __forceinline__ void softmax_blk(f32x16& p0, f32x16& p1, f32x16& o0, f32x16& o1, float& mhat, float& lrun, u32x4 (&pf)[4], bool first) {
;     ...
;         const float mn = first ? rm : fmaxf(rm, mhat); const float f = first ? 0.f : __builtin_amdgcn_exp2f(mhat - mn); mhat = mn; lrun *= f;
; #pragma unroll
;         for (int e = 0; e < 16; ++e) { o0[e] *= f; o1[e] *= f; }
;     }
;     float s0 = 0.f, s1 = 0.f;
; #pragma unroll
;     for (int e = 0; e < 16; ++e) { p0[e] = __builtin_amdgcn_exp2f(p0[e] - mhat); p1[e] = __builtin_amdgcn_exp2f(p1[e] - mhat); s0 += p0[e]; s1 += p1[e]; }
;     lrun += s0 + s1;
;     pf[0] = MLA_PACK(p0, 0); pf[1] = MLA_PACK(p0, 8); pf[2] = MLA_PACK(p1, 0); pf[3] = MLA_PACK(p1, 8);
; }
; __device__ __forceinline__ void pv_blk(const u32x4 (&pf)[4], f32x16& o0, f32x16& o1, LAS const unsigned char* vbase) {
; #pragma unroll
;     for (int ks = 0; ks < 4; ++ks) {
;         const bf16x8 p = __builtin_bit_cast(bf16x8, pf[ks]);
;         { const s16x4 lo = vtr(vbase + ks * 1024), hh = vtr(vbase + ks * 1024 + 512); const bf16x8 vf = {lo[0], lo[1], lo[2], lo[3], hh[0], hh[1], hh[2], hh[3]};
;           o0 = __builtin_amdgcn_mfma_f32_32x32x16_bf16(vf, p, o0, 0, 0, 0); }
;         { const s16x4 lo = vtr(vbase + 4096 + ks * 1024), hh = vtr(vbase + 4096 + ks * 1024 + 512); const bf16x8 vf = {lo[0], lo[1], lo[2], lo[3], hh[0], hh[1], hh[2], hh[3]};
;           o1 = __builtin_amdgcn_mfma_f32_32x32x16_bf16(vf, p, o1, 0, 0, 0); }
;     }
; }
.Lmla_rescBe_back:
	v_exp_f32_e32 v96, v96
	v_exp_f32_e32 v97, v97
	v_exp_f32_e32 v98, v98
	v_exp_f32_e32 v99, v99
	v_exp_f32_e32 v100, v100
	v_exp_f32_e32 v101, v101
	v_exp_f32_e32 v102, v102
	v_exp_f32_e32 v103, v103
	s_waitcnt lgkmcnt(4)
	v_mfma_f32_32x32x16_bf16 v[16:31], v[176:179], v[68:71], v[16:31]
	v_mfma_f32_32x32x16_bf16 v[0:15], v[180:183], v[68:71], v[0:15]
	ds_read_b64_tr_b16 v[176:177], v158 offset:37888
	ds_read_b64_tr_b16 v[178:179], v158 offset:38400
	ds_read_b64_tr_b16 v[180:181], v158 offset:41984
	ds_read_b64_tr_b16 v[182:183], v158 offset:42496
	v_add_f32_e32 v166, v96, v97
	v_add_f32_e32 v141, v141, v98
	v_add_f32_e32 v166, v166, v99
	v_cvt_pk_bf16_f32 v96, v96, v97
	v_cvt_pk_bf16_f32 v97, v98, v99
	v_exp_f32_e32 v104, v104
	v_exp_f32_e32 v105, v105
	v_exp_f32_e32 v106, v106
	v_exp_f32_e32 v107, v107
	v_add_f32_e32 v141, v141, v100
	v_add_f32_e32 v166, v166, v101
	v_add_f32_e32 v141, v141, v102
	v_add_f32_e32 v166, v166, v103
	v_cvt_pk_bf16_f32 v98, v100, v101
	v_cvt_pk_bf16_f32 v99, v102, v103
	v_exp_f32_e32 v108, v108
	v_exp_f32_e32 v109, v109
	v_exp_f32_e32 v110, v110
	v_exp_f32_e32 v111, v111
	v_add_f32_e32 v141, v141, v104
	v_add_f32_e32 v166, v166, v105
	v_add_f32_e32 v141, v141, v106
	v_add_f32_e32 v166, v166, v107
	s_waitcnt lgkmcnt(4)
	v_mfma_f32_32x32x16_bf16 v[16:31], v[128:131], v[72:75], v[16:31]
	v_mfma_f32_32x32x16_bf16 v[0:15], v[142:145], v[72:75], v[0:15]
	ds_read_b64_tr_b16 v[128:129], v158 offset:34816
	ds_read_b64_tr_b16 v[130:131], v158 offset:35328
	ds_read_b64_tr_b16 v[142:143], v158 offset:38912
	ds_read_b64_tr_b16 v[144:145], v158 offset:39424
	v_cvt_pk_bf16_f32 v100, v104, v105
	v_cvt_pk_bf16_f32 v101, v106, v107
	v_exp_f32_e32 v112, v112
	v_exp_f32_e32 v113, v113
	v_exp_f32_e32 v114, v114
	v_exp_f32_e32 v115, v115
	v_add_f32_e32 v141, v141, v108
	v_add_f32_e32 v166, v166, v109
	v_add_f32_e32 v141, v141, v110
	v_add_f32_e32 v166, v166, v111
	v_cvt_pk_bf16_f32 v102, v108, v109
	v_cvt_pk_bf16_f32 v103, v110, v111
	v_exp_f32_e32 v116, v116
	v_exp_f32_e32 v117, v117
	v_exp_f32_e32 v118, v118
	v_exp_f32_e32 v119, v119
	v_add_f32_e32 v141, v141, v112
	v_add_f32_e32 v166, v166, v113
	v_add_f32_e32 v141, v141, v114
	v_add_f32_e32 v166, v166, v115
	v_cvt_pk_bf16_f32 v104, v112, v113
	v_cvt_pk_bf16_f32 v105, v114, v115
	v_exp_f32_e32 v120, v120
	v_exp_f32_e32 v121, v121
	s_waitcnt lgkmcnt(4)
	v_mfma_f32_32x32x16_bf16 v[16:31], v[176:179], v[76:79], v[16:31]
	v_mfma_f32_32x32x16_bf16 v[0:15], v[180:183], v[76:79], v[0:15]
	ds_read_b64_tr_b16 v[176:177], v158 offset:35840
	ds_read_b64_tr_b16 v[178:179], v158 offset:36352
	ds_read_b64_tr_b16 v[180:181], v158 offset:39936
	ds_read_b64_tr_b16 v[182:183], v158 offset:40448
	v_exp_f32_e32 v122, v122
	v_exp_f32_e32 v123, v123
	v_add_f32_e32 v141, v141, v116
	v_add_f32_e32 v166, v166, v117
	v_add_f32_e32 v141, v141, v118
	v_add_f32_e32 v166, v166, v119
	v_cvt_pk_bf16_f32 v106, v116, v117
	v_cvt_pk_bf16_f32 v107, v118, v119
	v_exp_f32_e32 v124, v124
	v_exp_f32_e32 v125, v125
	v_exp_f32_e32 v126, v126
	v_exp_f32_e32 v127, v127
	v_add_f32_e32 v141, v141, v120
	v_add_f32_e32 v166, v166, v121
	v_add_f32_e32 v141, v141, v122
	v_add_f32_e32 v166, v166, v123
	v_cvt_pk_bf16_f32 v108, v120, v121
	v_cvt_pk_bf16_f32 v109, v122, v123
	v_add_f32_e32 v141, v141, v124
	v_add_f32_e32 v166, v166, v125
	v_add_f32_e32 v141, v141, v126
	v_add_f32_e32 v166, v166, v127
	v_cvt_pk_bf16_f32 v110, v124, v125
	v_cvt_pk_bf16_f32 v111, v126, v127
	v_add_f32_e32 v141, v141, v166
	s_waitcnt lgkmcnt(4)
	v_mfma_f32_32x32x16_bf16 v[48:63], v[128:131], v[96:99], v[48:63]
	v_mfma_f32_32x32x16_bf16 v[32:47], v[142:145], v[96:99], v[32:47]
	ds_read_b64_tr_b16 v[128:129], v158 offset:36864
	ds_read_b64_tr_b16 v[130:131], v158 offset:37376
	ds_read_b64_tr_b16 v[142:143], v158 offset:40960
	ds_read_b64_tr_b16 v[144:145], v158 offset:41472
	s_waitcnt lgkmcnt(4)
	v_mfma_f32_32x32x16_bf16 v[48:63], v[176:179], v[100:103], v[48:63]
	v_mfma_f32_32x32x16_bf16 v[32:47], v[180:183], v[100:103], v[32:47]
	ds_read_b64_tr_b16 v[176:177], v158 offset:37888
	ds_read_b64_tr_b16 v[178:179], v158 offset:38400
	ds_read_b64_tr_b16 v[180:181], v158 offset:41984
	ds_read_b64_tr_b16 v[182:183], v158 offset:42496
	s_waitcnt lgkmcnt(4)
	v_mfma_f32_32x32x16_bf16 v[48:63], v[128:131], v[104:107], v[48:63]
	v_mfma_f32_32x32x16_bf16 v[32:47], v[142:145], v[104:107], v[32:47]
	s_waitcnt lgkmcnt(0)
	v_mfma_f32_32x32x16_bf16 v[48:63], v[176:179], v[108:111], v[48:63]
	v_mfma_f32_32x32x16_bf16 v[32:47], v[180:183], v[108:111], v[32:47]
	s_waitcnt lgkmcnt(0)
	s_barrier
	s_setprio 0
	s_nop 7
	s_nop 3
	s_branch .LBB0_75
